# same A-tile-loads-first ordering applied to the P11 loop as well (P2 + P11)
# baseline (speedup 1.0000x reference)
.LBB0_1388:
	ds_read_b128 v[152:155], v149
	ds_read_b128 v[156:159], v149 offset:1024
	ds_read_b128 v[160:163], v149 offset:2048
	ds_read_b128 v[164:167], v149 offset:3072
	ds_read_b128 v[168:171], v150
	ds_read_b128 v[172:175], v150 offset:1024
	ds_read_b128 v[176:179], v150 offset:2048
	ds_read_b128 v[180:183], v150 offset:3072
	s_add_u32 s36, s28, 0x10000
	s_addc_u32 s37, s29, 0
	s_cmp_eq_u32 s59, 40
	s_cselect_b32 s41, s5, s37
	s_cselect_b32 s40, s4, s36
	s_cselect_b32 s39, s27, s58
	s_cselect_b32 s38, s26, s57
	v_lshl_add_u64 v[144:145], s[28:29], 0, v[136:137]
	s_add_i32 m0, s34, 0xc000
	ds_read_b128 v[184:187], v151
	ds_read_b128 v[190:193], v151 offset:1024
	ds_read_b128 v[194:197], v151 offset:2048
	ds_read_b128 v[198:201], v151 offset:3072
	ds_read_b128 v[202:205], v151 offset:4096
	ds_read_b128 v[206:209], v151 offset:5120
	ds_read_b128 v[210:213], v151 offset:6144
	ds_read_b128 v[214:217], v151 offset:7168
	global_load_lds_dwordx4 v[144:145], off
	v_lshl_add_u64 v[144:145], s[28:29], 0, v[138:139]
	s_add_i32 m0, s34, 0xe000
	s_nop 0
	global_load_lds_dwordx4 v[144:145], off
	s_waitcnt vmcnt(8)
	s_waitcnt lgkmcnt(0)
	s_barrier
	s_waitcnt lgkmcnt(0)
	v_mfma_f32_16x16x32_bf16 v[124:127], v[152:155], v[184:187], v[124:127]
	v_mfma_f32_16x16x32_bf16 v[120:123], v[160:163], v[184:187], v[120:123]
	v_mfma_f32_16x16x32_bf16 v[116:119], v[152:155], v[194:197], v[116:119]
	v_mfma_f32_16x16x32_bf16 v[108:111], v[160:163], v[194:197], v[108:111]
	v_mfma_f32_16x16x32_bf16 v[100:103], v[152:155], v[202:205], v[100:103]
	v_mfma_f32_16x16x32_bf16 v[92:95], v[160:163], v[202:205], v[92:95]
	v_mfma_f32_16x16x32_bf16 v[84:87], v[152:155], v[210:213], v[84:87]
	v_mfma_f32_16x16x32_bf16 v[76:79], v[160:163], v[210:213], v[76:79]
	v_mfma_f32_16x16x32_bf16 v[124:127], v[156:159], v[190:193], v[124:127]
	v_mfma_f32_16x16x32_bf16 v[120:123], v[164:167], v[190:193], v[120:123]
	v_mfma_f32_16x16x32_bf16 v[116:119], v[156:159], v[198:201], v[116:119]
	v_mfma_f32_16x16x32_bf16 v[108:111], v[164:167], v[198:201], v[108:111]
	v_mfma_f32_16x16x32_bf16 v[100:103], v[156:159], v[206:209], v[100:103]
	v_mfma_f32_16x16x32_bf16 v[92:95], v[164:167], v[206:209], v[92:95]
	v_mfma_f32_16x16x32_bf16 v[84:87], v[156:159], v[214:217], v[84:87]
	v_mfma_f32_16x16x32_bf16 v[76:79], v[164:167], v[214:217], v[76:79]
	v_mfma_f32_16x16x32_bf16 v[112:115], v[168:171], v[184:187], v[112:115]
	v_mfma_f32_16x16x32_bf16 v[104:107], v[176:179], v[184:187], v[104:107]
	v_mfma_f32_16x16x32_bf16 v[96:99], v[168:171], v[194:197], v[96:99]
	v_mfma_f32_16x16x32_bf16 v[88:91], v[176:179], v[194:197], v[88:91]
	v_mfma_f32_16x16x32_bf16 v[80:83], v[168:171], v[202:205], v[80:83]
	v_mfma_f32_16x16x32_bf16 v[72:75], v[176:179], v[202:205], v[72:75]
	v_mfma_f32_16x16x32_bf16 v[68:71], v[168:171], v[210:213], v[68:71]
	v_mfma_f32_16x16x32_bf16 v[64:67], v[176:179], v[210:213], v[64:67]
	v_mfma_f32_16x16x32_bf16 v[112:115], v[172:175], v[190:193], v[112:115]
	v_mfma_f32_16x16x32_bf16 v[104:107], v[180:183], v[190:193], v[104:107]
	v_mfma_f32_16x16x32_bf16 v[96:99], v[172:175], v[198:201], v[96:99]
	v_mfma_f32_16x16x32_bf16 v[88:91], v[180:183], v[198:201], v[88:91]
	v_mfma_f32_16x16x32_bf16 v[80:83], v[172:175], v[206:209], v[80:83]
	v_mfma_f32_16x16x32_bf16 v[72:75], v[180:183], v[206:209], v[72:75]
	v_mfma_f32_16x16x32_bf16 v[68:71], v[172:175], v[214:217], v[68:71]
	v_mfma_f32_16x16x32_bf16 v[64:67], v[180:183], v[214:217], v[64:67]
	s_barrier
	v_lshl_add_u64 v[220:221], s[40:41], 0, v[128:129]
	s_mov_b32 m0, s34
	v_lshl_add_u64 v[222:223], s[40:41], 0, v[132:133]
	global_load_lds_dwordx4 v[220:221], off
	s_mov_b32 m0, s35
	s_nop 0
	global_load_lds_dwordx4 v[222:223], off
	ds_read_b128 v[184:187], v151 offset:16384
	ds_read_b128 v[190:193], v151 offset:17408
	ds_read_b128 v[194:197], v151 offset:18432
	ds_read_b128 v[198:201], v151 offset:19456
	ds_read_b128 v[202:205], v151 offset:20480
	ds_read_b128 v[206:209], v151 offset:21504
	ds_read_b128 v[210:213], v151 offset:22528
	ds_read_b128 v[214:217], v151 offset:23552
	s_add_i32 s28, s47, s13
	v_lshl_add_u64 v[144:145], s[38:39], 0, v[130:131]
	s_mov_b32 m0, s28
	s_nop 0
	global_load_lds_dwordx4 v[144:145], off
	s_add_i32 m0, s28, 0x2000
	s_add_u32 s28, s38, 0xb0000
	v_lshl_add_u64 v[218:219], s[38:39], 0, v[134:135]
	s_addc_u32 s29, s39, 0
	s_add_i32 s33, s48, s13
	global_load_lds_dwordx4 v[218:219], off
	v_lshl_add_u64 v[224:225], s[28:29], 0, v[130:131]
	s_mov_b32 m0, s33
	s_nop 0
	global_load_lds_dwordx4 v[224:225], off
	v_lshl_add_u64 v[224:225], s[28:29], 0, v[134:135]
	s_add_i32 m0, s33, 0x2000
	s_nop 0
	global_load_lds_dwordx4 v[224:225], off
	s_waitcnt vmcnt(8)
	s_waitcnt lgkmcnt(0)
	s_barrier
	s_waitcnt lgkmcnt(0)
	v_mfma_f32_16x16x32_bf16 v[60:63], v[152:155], v[184:187], v[60:63]
	v_mfma_f32_16x16x32_bf16 v[56:59], v[160:163], v[184:187], v[56:59]
	v_mfma_f32_16x16x32_bf16 v[52:55], v[152:155], v[194:197], v[52:55]
	v_mfma_f32_16x16x32_bf16 v[44:47], v[160:163], v[194:197], v[44:47]
	v_mfma_f32_16x16x32_bf16 v[36:39], v[152:155], v[202:205], v[36:39]
	v_mfma_f32_16x16x32_bf16 v[28:31], v[160:163], v[202:205], v[28:31]
	v_mfma_f32_16x16x32_bf16 v[20:23], v[152:155], v[210:213], v[20:23]
	v_mfma_f32_16x16x32_bf16 v[12:15], v[160:163], v[210:213], v[12:15]
	v_mfma_f32_16x16x32_bf16 v[60:63], v[156:159], v[190:193], v[60:63]
	v_mfma_f32_16x16x32_bf16 v[56:59], v[164:167], v[190:193], v[56:59]
	v_mfma_f32_16x16x32_bf16 v[52:55], v[156:159], v[198:201], v[52:55]
	v_mfma_f32_16x16x32_bf16 v[44:47], v[164:167], v[198:201], v[44:47]
	v_mfma_f32_16x16x32_bf16 v[36:39], v[156:159], v[206:209], v[36:39]
	v_mfma_f32_16x16x32_bf16 v[28:31], v[164:167], v[206:209], v[28:31]
	v_mfma_f32_16x16x32_bf16 v[20:23], v[156:159], v[214:217], v[20:23]
	v_mfma_f32_16x16x32_bf16 v[12:15], v[164:167], v[214:217], v[12:15]
	v_mfma_f32_16x16x32_bf16 v[48:51], v[168:171], v[184:187], v[48:51]
	v_mfma_f32_16x16x32_bf16 v[40:43], v[176:179], v[184:187], v[40:43]
	v_mfma_f32_16x16x32_bf16 v[32:35], v[168:171], v[194:197], v[32:35]
	v_mfma_f32_16x16x32_bf16 v[24:27], v[176:179], v[194:197], v[24:27]
	v_mfma_f32_16x16x32_bf16 v[16:19], v[168:171], v[202:205], v[16:19]
	v_mfma_f32_16x16x32_bf16 v[8:11], v[176:179], v[202:205], v[8:11]
	v_mfma_f32_16x16x32_bf16 v[4:7], v[168:171], v[210:213], v[4:7]
	v_mfma_f32_16x16x32_bf16 v[0:3], v[176:179], v[210:213], v[0:3]
	v_mfma_f32_16x16x32_bf16 v[48:51], v[172:175], v[190:193], v[48:51]
	v_mfma_f32_16x16x32_bf16 v[40:43], v[180:183], v[190:193], v[40:43]
	v_mfma_f32_16x16x32_bf16 v[32:35], v[172:175], v[198:201], v[32:35]
	v_mfma_f32_16x16x32_bf16 v[24:27], v[180:183], v[198:201], v[24:27]
	v_mfma_f32_16x16x32_bf16 v[16:19], v[172:175], v[206:209], v[16:19]
	v_mfma_f32_16x16x32_bf16 v[8:11], v[180:183], v[206:209], v[8:11]
	v_mfma_f32_16x16x32_bf16 v[4:7], v[172:175], v[214:217], v[4:7]
	v_mfma_f32_16x16x32_bf16 v[0:3], v[180:183], v[214:217], v[0:3]
	s_barrier
	s_add_i32 s33, 0, 0x18000
	s_add_i32 s60, 0, 0x1c000
	v_add_u32_e32 v164, s33, v147
	v_add_u32_e32 v180, s60, v147
	ds_read_b128 v[152:155], v164
	ds_read_b128 v[156:159], v164 offset:1024
	ds_read_b128 v[160:163], v164 offset:2048
	ds_read_b128 v[164:167], v164 offset:3072
	ds_read_b128 v[168:171], v180
	ds_read_b128 v[172:175], v180 offset:1024
	ds_read_b128 v[176:179], v180 offset:2048
	ds_read_b128 v[180:183], v180 offset:3072
	s_add_u32 s28, s40, 0x4000
	s_addc_u32 s29, s41, 0
	s_mov_b32 m0, s42
	v_lshl_add_u64 v[224:225], s[28:29], 0, v[128:129]
	ds_read_b128 v[184:187], v151 offset:32768
	ds_read_b128 v[190:193], v151 offset:33792
	ds_read_b128 v[194:197], v151 offset:34816
	ds_read_b128 v[198:201], v151 offset:35840
	ds_read_b128 v[202:205], v151 offset:36864
	ds_read_b128 v[206:209], v151 offset:37888
	ds_read_b128 v[210:213], v151 offset:38912
	ds_read_b128 v[214:217], v151 offset:39936
	global_load_lds_dwordx4 v[224:225], off
	v_lshl_add_u64 v[224:225], s[28:29], 0, v[132:133]
	s_mov_b32 m0, s43
	s_nop 0
	global_load_lds_dwordx4 v[224:225], off
	s_waitcnt vmcnt(8)
	s_waitcnt lgkmcnt(0)
	s_nop 0
	s_barrier
	s_waitcnt lgkmcnt(0)
	v_mfma_f32_16x16x32_bf16 v[124:127], v[152:155], v[184:187], v[124:127]
	v_mfma_f32_16x16x32_bf16 v[120:123], v[160:163], v[184:187], v[120:123]
	v_mfma_f32_16x16x32_bf16 v[116:119], v[152:155], v[194:197], v[116:119]
	v_mfma_f32_16x16x32_bf16 v[108:111], v[160:163], v[194:197], v[108:111]
	v_mfma_f32_16x16x32_bf16 v[100:103], v[152:155], v[202:205], v[100:103]
	v_mfma_f32_16x16x32_bf16 v[92:95], v[160:163], v[202:205], v[92:95]
	v_mfma_f32_16x16x32_bf16 v[84:87], v[152:155], v[210:213], v[84:87]
	v_mfma_f32_16x16x32_bf16 v[76:79], v[160:163], v[210:213], v[76:79]
	v_mfma_f32_16x16x32_bf16 v[124:127], v[156:159], v[190:193], v[124:127]
	v_mfma_f32_16x16x32_bf16 v[120:123], v[164:167], v[190:193], v[120:123]
	v_mfma_f32_16x16x32_bf16 v[116:119], v[156:159], v[198:201], v[116:119]
	v_mfma_f32_16x16x32_bf16 v[108:111], v[164:167], v[198:201], v[108:111]
	v_mfma_f32_16x16x32_bf16 v[100:103], v[156:159], v[206:209], v[100:103]
	v_mfma_f32_16x16x32_bf16 v[92:95], v[164:167], v[206:209], v[92:95]
	v_mfma_f32_16x16x32_bf16 v[84:87], v[156:159], v[214:217], v[84:87]
	v_mfma_f32_16x16x32_bf16 v[76:79], v[164:167], v[214:217], v[76:79]
	v_mfma_f32_16x16x32_bf16 v[112:115], v[168:171], v[184:187], v[112:115]
	v_mfma_f32_16x16x32_bf16 v[104:107], v[176:179], v[184:187], v[104:107]
	v_mfma_f32_16x16x32_bf16 v[96:99], v[168:171], v[194:197], v[96:99]
	v_mfma_f32_16x16x32_bf16 v[88:91], v[176:179], v[194:197], v[88:91]
	v_mfma_f32_16x16x32_bf16 v[80:83], v[168:171], v[202:205], v[80:83]
	v_mfma_f32_16x16x32_bf16 v[72:75], v[176:179], v[202:205], v[72:75]
	v_mfma_f32_16x16x32_bf16 v[68:71], v[168:171], v[210:213], v[68:71]
	v_mfma_f32_16x16x32_bf16 v[64:67], v[176:179], v[210:213], v[64:67]
	v_mfma_f32_16x16x32_bf16 v[112:115], v[172:175], v[190:193], v[112:115]
	v_mfma_f32_16x16x32_bf16 v[104:107], v[180:183], v[190:193], v[104:107]
	v_mfma_f32_16x16x32_bf16 v[96:99], v[172:175], v[198:201], v[96:99]
	v_mfma_f32_16x16x32_bf16 v[88:91], v[180:183], v[198:201], v[88:91]
	v_mfma_f32_16x16x32_bf16 v[80:83], v[172:175], v[206:209], v[80:83]
	v_mfma_f32_16x16x32_bf16 v[72:75], v[180:183], v[206:209], v[72:75]
	v_mfma_f32_16x16x32_bf16 v[68:71], v[172:175], v[214:217], v[68:71]
	v_mfma_f32_16x16x32_bf16 v[64:67], v[180:183], v[214:217], v[64:67]
	s_barrier
	v_lshl_add_u64 v[144:145], v[220:221], 0, s[92:93]
	s_mov_b32 m0, s45
	s_nop 0
	global_load_lds_dwordx4 v[144:145], off
	v_lshl_add_u64 v[144:145], v[222:223], 0, s[92:93]
	s_mov_b32 m0, s46
	s_nop 0
	global_load_lds_dwordx4 v[144:145], off
	ds_read_b128 v[184:187], v151 offset:49152
	ds_read_b128 v[190:193], v151 offset:50176
	ds_read_b128 v[194:197], v151 offset:51200
	ds_read_b128 v[198:201], v151 offset:52224
	ds_read_b128 v[202:205], v151 offset:53248
	ds_read_b128 v[206:209], v151 offset:54272
	ds_read_b128 v[210:213], v151 offset:55296
	ds_read_b128 v[214:217], v151 offset:56320
	s_add_i32 s28, s33, s13
	s_add_u32 s62, s38, 0x80
	s_addc_u32 s63, s39, 0
	v_lshl_add_u64 v[144:145], s[62:63], 0, v[130:131]
	s_mov_b32 m0, s28
	s_nop 0
	global_load_lds_dwordx4 v[144:145], off
	v_lshl_add_u64 v[144:145], s[62:63], 0, v[134:135]
	s_add_i32 m0, s28, 0x2000
	s_nop 0
	global_load_lds_dwordx4 v[144:145], off
	s_add_u32 s28, s38, 0xb0080
	s_addc_u32 s29, s39, 0
	s_add_i32 s33, s60, s13
	v_lshl_add_u64 v[144:145], s[28:29], 0, v[130:131]
	s_mov_b32 m0, s33
	s_nop 0
	global_load_lds_dwordx4 v[144:145], off
	v_lshl_add_u64 v[144:145], s[28:29], 0, v[134:135]
	s_add_i32 m0, s33, 0x2000
	s_nop 0
	global_load_lds_dwordx4 v[144:145], off
	s_waitcnt vmcnt(8)
	s_waitcnt lgkmcnt(0)
	s_nop 0
	s_barrier
	s_waitcnt lgkmcnt(0)
	v_mfma_f32_16x16x32_bf16 v[60:63], v[152:155], v[184:187], v[60:63]
	v_mfma_f32_16x16x32_bf16 v[56:59], v[160:163], v[184:187], v[56:59]
	v_mfma_f32_16x16x32_bf16 v[52:55], v[152:155], v[194:197], v[52:55]
	v_mfma_f32_16x16x32_bf16 v[44:47], v[160:163], v[194:197], v[44:47]
	v_mfma_f32_16x16x32_bf16 v[36:39], v[152:155], v[202:205], v[36:39]
	v_mfma_f32_16x16x32_bf16 v[28:31], v[160:163], v[202:205], v[28:31]
	v_mfma_f32_16x16x32_bf16 v[20:23], v[152:155], v[210:213], v[20:23]
	v_mfma_f32_16x16x32_bf16 v[12:15], v[160:163], v[210:213], v[12:15]
	v_mfma_f32_16x16x32_bf16 v[60:63], v[156:159], v[190:193], v[60:63]
	v_mfma_f32_16x16x32_bf16 v[56:59], v[164:167], v[190:193], v[56:59]
	v_mfma_f32_16x16x32_bf16 v[52:55], v[156:159], v[198:201], v[52:55]
	v_mfma_f32_16x16x32_bf16 v[44:47], v[164:167], v[198:201], v[44:47]
	v_mfma_f32_16x16x32_bf16 v[36:39], v[156:159], v[206:209], v[36:39]
	v_mfma_f32_16x16x32_bf16 v[28:31], v[164:167], v[206:209], v[28:31]
	v_mfma_f32_16x16x32_bf16 v[20:23], v[156:159], v[214:217], v[20:23]
	v_mfma_f32_16x16x32_bf16 v[12:15], v[164:167], v[214:217], v[12:15]
	v_mfma_f32_16x16x32_bf16 v[48:51], v[168:171], v[184:187], v[48:51]
	v_mfma_f32_16x16x32_bf16 v[40:43], v[176:179], v[184:187], v[40:43]
	v_mfma_f32_16x16x32_bf16 v[32:35], v[168:171], v[194:197], v[32:35]
	v_mfma_f32_16x16x32_bf16 v[24:27], v[176:179], v[194:197], v[24:27]
	v_mfma_f32_16x16x32_bf16 v[16:19], v[168:171], v[202:205], v[16:19]
	v_mfma_f32_16x16x32_bf16 v[8:11], v[176:179], v[202:205], v[8:11]
	v_mfma_f32_16x16x32_bf16 v[4:7], v[168:171], v[210:213], v[4:7]
	v_mfma_f32_16x16x32_bf16 v[0:3], v[176:179], v[210:213], v[0:3]
	v_mfma_f32_16x16x32_bf16 v[48:51], v[172:175], v[190:193], v[48:51]
	v_mfma_f32_16x16x32_bf16 v[40:43], v[180:183], v[190:193], v[40:43]
	v_mfma_f32_16x16x32_bf16 v[32:35], v[172:175], v[198:201], v[32:35]
	v_mfma_f32_16x16x32_bf16 v[24:27], v[180:183], v[198:201], v[24:27]
	v_mfma_f32_16x16x32_bf16 v[16:19], v[172:175], v[206:209], v[16:19]
	v_mfma_f32_16x16x32_bf16 v[8:11], v[180:183], v[206:209], v[8:11]
	v_mfma_f32_16x16x32_bf16 v[4:7], v[172:175], v[214:217], v[4:7]
	v_mfma_f32_16x16x32_bf16 v[0:3], v[180:183], v[214:217], v[0:3]
	s_barrier
	s_add_i32 s59, s59, 2
	s_add_u32 s57, s57, 0x100
	s_addc_u32 s58, s58, 0
	s_cmp_gt_u32 s59, 41
	s_mov_b64 s[28:29], s[36:37]
	s_cbranch_scc0 .LBB0_1388
	s_and_b64 vcc, exec, s[10:11]
	s_cbranch_vccz .LBB0_1391
	s_barrier
